# v061 + XCD-local grid barrier (no L2 write-back, no cross-XCD round) on 3 row-panel-local GEMM->GEMM boundaries (L0 out->up, up->down; L1 up->down), enabled by a run-time placement check
# speedup vs baseline: 1.0166x; 1.0018x over previous
; #define LAS __attribute__((address_space(3)))
;     __device__ __forceinline__ unsigned char* ws() const { return *(const __attribute__((address_space(4))) ucptr_t*)(p + 264); }
; __device__ __forceinline__ unsigned xb_add(unsigned* p, unsigned v) { return __hip_atomic_fetch_add(p, v, __ATOMIC_RELAXED, __HIP_MEMORY_SCOPE_AGENT); }
; __device__ __forceinline__ unsigned xb_xcc_id() { return (unsigned)__builtin_amdgcn_s_getreg((3 << 11) | 20) & 0xFu; }
; __device__ __forceinline__ XcdBarrier xcd_barrier_post(unsigned* bar, volatile LAS unsigned* st) {
;     XcdBarrier b; b.bar = bar; b.x = xb_xcc_id(); b.st = st;
;     if (threadIdx.x == 0) (void)xb_add(&bar[XB_XCNT(b.x)], 1u);
;     return b;
; }
; __global__ void __launch_bounds__(NTHREADS, 2) mega_fwd(Args args) {
;     extern __shared__ __attribute__((aligned(16))) unsigned char lds[];
;     ...
;     volatile LAS unsigned* misc = (volatile LAS unsigned*)((LAS unsigned char*)lds + MISC_OFF);
;     if (threadIdx.x < 32) misc[threadIdx.x] = 0u;
;     __syncthreads();
;     XcdBarrier bar = xcd_barrier_post((unsigned*)(args.ws + WS_CTL) + CW_BAR, misc + 8);
_Z8mega_fwd4Args:
	v_and_b32_e32 v1, 0x3ff, v0
	v_writelane_b32 v253, s0, 0
	s_load_dwordx4 s[68:71], s[0:1], 0x108
	s_mov_b32 s86, s2
	v_writelane_b32 v253, s1, 1
	v_cmp_gt_u32_e32 vcc, 32, v1
	s_and_saveexec_b64 s[0:1], vcc
	v_lshl_add_u32 v2, v1, 2, 0
	v_add_u32_e32 v2, 0x23f80, v2
	v_mov_b32_e32 v3, 0
	ds_write_b32 v2, v3
	s_or_b64 exec, exec, s[0:1]
	s_waitcnt lgkmcnt(0)
	s_add_u32 s0, s68, 0x4000
	s_addc_u32 s1, s69, 0
	v_writelane_b32 v253, s0, 2
	s_barrier
	s_nop 0
	v_writelane_b32 v253, s1, 3
	s_getreg_b32 s0, hwreg(HW_REG_XCC_ID, 0, 4)
	s_and_b32 s4, s0, 15
	v_cmp_eq_u32_e32 vcc, 0, v1
	s_and_saveexec_b64 s[0:1], vcc
	s_cbranch_execz .LBB0_5
	s_mov_b64 s[2:3], exec
	v_mbcnt_lo_u32_b32 v2, s2, 0
	v_mbcnt_hi_u32_b32 v2, s3, v2
	v_cmp_eq_u32_e32 vcc, 0, v2
	s_and_b64 s[6:7], exec, vcc
	s_mov_b64 exec, s[6:7]
	s_cbranch_execz .LBB0_5
	s_bcnt1_i32_b64 s2, s[2:3]
	s_lshl_b32 s5, s4, 8
	v_mov_b32_e32 v3, s2
	v_readlane_b32 s2, v253, 2
	v_mov_b32_e32 v2, s5
	v_readlane_b32 s3, v253, 3
	s_nop 4
	global_atomic_add v2, v3, s[2:3] offset:1024
	s_and_b32 s5, s86, 7
	s_lshl_b32 s5, s5, 2
	v_mov_b32_e32 v4, s5
	s_lshl_b32 s5, 1, s4
	v_mov_b32_e32 v5, s5
	s_nop 0
	global_atomic_or v4, v5, s[2:3]

; __device__ __forceinline__ unsigned xb_ld(unsigned* p)              { return __hip_atomic_load(p, __ATOMIC_RELAXED, __HIP_MEMORY_SCOPE_AGENT); }
; __device__ __forceinline__ unsigned xb_add(unsigned* p, unsigned v) { return __hip_atomic_fetch_add(p, v, __ATOMIC_RELAXED, __HIP_MEMORY_SCOPE_AGENT); }
; #define XB_SPIN(cond, bar) do { unsigned _sp = 0; while (cond) { __builtin_amdgcn_s_sleep(1); \
;     if ((++_sp & 255u) == 0u) { if (xb_ld(&(bar)[XB_TMO])) break; if (_sp > XB_SPIN_CAP) { atomicAdd(&(bar)[XB_TMO], 1u); break; } } } } while (0)
; __device__ __forceinline__ void xcd_barrier(const XcdBarrier& b, int tid_in) {
;     asm volatile("s_waitcnt vmcnt(0)" ::: "memory");
;     __syncthreads();
;     if (tid_in < 64) { if (b.st[0] == 0u) { unsigned nl_, nx_; xcd_barrier_complete_wave(b.bar, b.x, tid_in, nl_, nx_); if (tid_in == 0) { b.st[0] = nl_; b.st[1] = nx_; } asm volatile("s_waitcnt lgkmcnt(0)" ::: "memory"); } }
;     if (tid_in == 0) {
;         unsigned* bar = b.bar;
;         __builtin_amdgcn_s_waitcnt(0);
;         unsigned nloc = b.st[0], nx = b.st[1];
;         if (nloc == 0u) { xcd_barrier_complete(bar, b.x, nloc, nx); b.st[0] = nloc; b.st[1] = nx; }
;         const unsigned old = xb_add(&bar[XB_XSUB(b.x)], 1u);
;         const unsigned gen = old / nloc;
;         if (old + 1u == (gen + 1u) * nloc) {
;             __builtin_amdgcn_fence(__ATOMIC_RELEASE, "agent");
;             asm volatile("s_waitcnt vmcnt(0)" ::: "memory");
;             const unsigned og = xb_add(&bar[XB_TOP], 1u);
;             const unsigned tg = og / nx;
;             if (og + 1u == (tg + 1u) * nx) xb_add(&bar[XB_TOPGEN], 1u);
;             else XB_SPIN(xb_ld(&bar[XB_TOPGEN]) == tg, bar);
;             __builtin_amdgcn_fence(__ATOMIC_ACQUIRE, "agent");
;             xb_add(&bar[XB_XGEN(b.x)], 1u);
;             asm volatile("s_waitcnt vmcnt(0)" ::: "memory");
;         } else {
;             XB_SPIN(xb_ld(&bar[XB_XGEN(b.x)]) == gen, bar);
.LBB0_531:
	s_cmp_lg_u32 s70, 2
	s_cbranch_scc1 .Lxb_s2done
	v_readlane_b32 s4, v253, 55
	s_and_b32 s4, s4, 7
	s_lshl_b32 s4, s4, 2
	v_mov_b32_e32 v16, s4
	s_nop 0
	global_load_dword v18, v16, s[0:1] sc1
	s_waitcnt vmcnt(0)
	v_readfirstlane_b32 s4, v18
	v_readfirstlane_b32 s5, v2
	s_bcnt1_i32_b32 s4, s4
	s_cmp_lg_u32 s4, 1
	s_cbranch_scc1 .Lxb_viol
	s_cmp_eq_u32 s5, 32
	s_cbranch_scc1 .Lxb_s2done
.Lxb_viol:
	v_mov_b32_e32 v16, 0
	s_nop 0
	global_atomic_add v16, v221, s[0:1] offset:64
	s_waitcnt vmcnt(0)
.Lxb_s2done:
	v_mov_b32_e32 v16, 0
	s_nop 0
	global_load_dword v18, v16, s[0:1] offset:64 sc1
	v_readlane_b32 s4, v253, 41
	s_add_u32 s26, s0, s4
	s_addc_u32 s25, s1, 0
	v_mov_b32_e32 v1, s26
	v_add_co_u32_e32 v4, vcc, 0x1000, v1
	v_mov_b32_e32 v1, s25
	s_nop 0
	v_addc_co_u32_e32 v5, vcc, 0, v1, vcc
	flat_atomic_add v3, v[4:5], v221 offset:1024 sc0
	v_cvt_f32_u32_e32 v1, v2
	v_sub_u32_e32 v4, 0, v2
	v_rcp_iflag_f32_e32 v1, v1
	s_nop 0
	v_mul_f32_e32 v1, 0x4f7ffffe, v1
	v_cvt_u32_f32_e32 v1, v1
	v_mul_lo_u32 v4, v4, v1
	v_mul_hi_u32 v4, v1, v4
	v_add_u32_e32 v1, v1, v4
	s_waitcnt vmcnt(0) lgkmcnt(0)
	v_mul_hi_u32 v1, v3, v1
	v_mul_lo_u32 v4, v1, v2
	v_sub_u32_e32 v4, v3, v4
	v_cmp_ge_u32_e32 vcc, v4, v2
	v_add_u32_e32 v5, 1, v1
	s_nop 0
	v_cndmask_b32_e32 v1, v1, v5, vcc
	v_sub_u32_e32 v5, v4, v2
	v_cndmask_b32_e32 v4, v4, v5, vcc
	v_cmp_ge_u32_e32 vcc, v4, v2
	v_add_u32_e32 v4, 1, v1
	s_nop 0
	v_cndmask_b32_e32 v1, v1, v4, vcc
	v_add_u32_e32 v4, 1, v3
	v_mad_u64_u32 v[2:3], s[4:5], v2, v1, v[2:3]
	v_cmp_ne_u32_e32 vcc, v4, v2
	s_and_saveexec_b64 s[4:5], vcc
	s_xor_b64 s[4:5], exec, s[4:5]
	s_cbranch_execz .LBB0_552
	buffer_inv sc1
	v_mov_b32_e32 v0, s26
	v_add_co_u32_e32 v2, vcc, 0x2000, v0
	v_mov_b32_e32 v0, s25
	s_nop 0
	v_addc_co_u32_e32 v3, vcc, 0, v0, vcc
	flat_load_dword v0, v[2:3] offset:1024 sc1
	s_add_u32 s8, s26, 0x2400
	s_addc_u32 s9, s25, 0
	s_waitcnt vmcnt(0) lgkmcnt(0)
	v_cmp_eq_u32_e32 vcc, v0, v1
	s_and_saveexec_b64 s[6:7], vcc
	s_cbranch_execz .LBB0_551
	s_mov_b32 s27, 1
	s_mov_b64 s[10:11], 0
	s_branch .LBB0_535

; __device__ __forceinline__ unsigned xb_ld(unsigned* p)              { return __hip_atomic_load(p, __ATOMIC_RELAXED, __HIP_MEMORY_SCOPE_AGENT); }
; __device__ __forceinline__ unsigned xb_add(unsigned* p, unsigned v) { return __hip_atomic_fetch_add(p, v, __ATOMIC_RELAXED, __HIP_MEMORY_SCOPE_AGENT); }
; #define XB_SPIN(cond, bar) do { unsigned _sp = 0; while (cond) { __builtin_amdgcn_s_sleep(1); \
;     if ((++_sp & 255u) == 0u) { if (xb_ld(&(bar)[XB_TMO])) break; if (_sp > XB_SPIN_CAP) { atomicAdd(&(bar)[XB_TMO], 1u); break; } } } } while (0)
; __device__ __forceinline__ void xcd_barrier(const XcdBarrier& b, int tid_in) {
;     ...
;     if (tid_in == 0) {
;         unsigned* bar = b.bar;
;         __builtin_amdgcn_s_waitcnt(0);
;         unsigned nloc = b.st[0], nx = b.st[1];
;         if (nloc == 0u) { xcd_barrier_complete(bar, b.x, nloc, nx); b.st[0] = nloc; b.st[1] = nx; }
;         const unsigned old = xb_add(&bar[XB_XSUB(b.x)], 1u);
;         const unsigned gen = old / nloc;
;         if (old + 1u == (gen + 1u) * nloc) {
;             __builtin_amdgcn_fence(__ATOMIC_RELEASE, "agent");
;             asm volatile("s_waitcnt vmcnt(0)" ::: "memory");
;             const unsigned og = xb_add(&bar[XB_TOP], 1u);
;             const unsigned tg = og / nx;
;             if (og + 1u == (tg + 1u) * nx) xb_add(&bar[XB_TOPGEN], 1u);
;             else XB_SPIN(xb_ld(&bar[XB_TOPGEN]) == tg, bar);
;             __builtin_amdgcn_fence(__ATOMIC_ACQUIRE, "agent");
;             xb_add(&bar[XB_XGEN(b.x)], 1u);
;             asm volatile("s_waitcnt vmcnt(0)" ::: "memory");
.LBB0_552:
	s_andn2_saveexec_b64 s[4:5], s[4:5]
	s_cbranch_execz .LBB0_8
	s_add_i32 s4, s70, -2
	s_cmp_lt_u32 s4, 15
	s_cbranch_scc0 .Lxb_global
	s_lshr_b32 s5, 0x4060, s4
	s_and_b32 s5, s5, 1
	s_cbranch_scc0 .Lxb_global
	v_readfirstlane_b32 s5, v18
	s_cmp_eq_u32 s5, 0
	s_cbranch_scc0 .Lxb_global
	s_mov_b64 s[0:1], exec
	s_branch .LBB0_7
.Lxb_global:
	v_mov_b32_e32 v1, s0
	v_add_co_u32_e32 v2, vcc, 0x3000, v1
	v_mov_b32_e32 v1, s1
	buffer_wbl2 sc1
	s_waitcnt vmcnt(0)
	v_addc_co_u32_e32 v3, vcc, 0, v1, vcc
	flat_atomic_add v1, v[2:3], v221 offset:1024 sc0
	v_cvt_f32_u32_e32 v2, v0
	v_sub_u32_e32 v3, 0, v0
	s_mov_b64 s[8:9], -1
	v_rcp_iflag_f32_e32 v2, v2
	s_nop 0
	v_mul_f32_e32 v2, 0x4f7ffffe, v2
	v_cvt_u32_f32_e32 v2, v2
	v_mul_lo_u32 v3, v3, v2
	v_mul_hi_u32 v3, v2, v3
	v_add_u32_e32 v2, v2, v3
	s_waitcnt vmcnt(0) lgkmcnt(0)
	v_mul_hi_u32 v2, v1, v2
	v_mul_lo_u32 v3, v2, v0
	v_sub_u32_e32 v3, v1, v3
	v_cmp_ge_u32_e32 vcc, v3, v0
	v_add_u32_e32 v4, 1, v2
	s_nop 0
	v_cndmask_b32_e32 v2, v2, v4, vcc
	v_sub_u32_e32 v4, v3, v0
	v_cndmask_b32_e32 v3, v3, v4, vcc
	v_cmp_ge_u32_e32 vcc, v3, v0
	v_add_u32_e32 v3, 1, v2
	s_nop 0
	v_cndmask_b32_e32 v2, v2, v3, vcc
	v_add_u32_e32 v3, 1, v1
	v_mad_u64_u32 v[0:1], s[4:5], v0, v2, v[0:1]
	s_add_u32 s4, s0, 0x3500
	s_addc_u32 s5, s1, 0
	v_cmp_ne_u32_e32 vcc, v3, v0
	v_mov_b64_e32 v[0:1], s[4:5]
	s_and_saveexec_b64 s[6:7], vcc
	s_cbranch_execz .LBB0_565
	buffer_inv sc1
	v_mov_b64_e32 v[0:1], s[4:5]
	flat_load_dword v0, v[0:1] sc1
	s_mov_b64 s[12:13], 0
	s_waitcnt vmcnt(0) lgkmcnt(0)
	v_cmp_eq_u32_e32 vcc, v0, v2
	s_and_saveexec_b64 s[10:11], vcc
	s_cbranch_execz .LBB0_564
	s_add_u32 s8, s0, 0x200
	s_addc_u32 s9, s1, 0
	s_mov_b32 s22, 1
	s_mov_b64 s[0:1], 0
	s_branch .LBB0_557
